# attention-unit epilogue dwordx2 stores (OAB) coalesced via ds_bpermute lane permutation, on top of v019
# baseline (speedup 1.0000x reference)
; DEVI unsigned pk_bf16(float lo, float hi) { const f32x2_t v = {lo, hi}; const bf16x2_t b = __builtin_convertvector(v, bf16x2_t); return __builtin_bit_cast(unsigned, b); }
; DEVI float bf_lo(unsigned u) { return __uint_as_float(u << 16); }
; DEVI float bf_hi(unsigned u) { return __uint_as_float(u & 0xffff0000u); }
; DEVI float shx(float v, int m) { return __shfl_xor(v, m); }
; template <int MODE, bool SAMPLE>
; DEVI void attn_unit(const Params& p, const int b, const int h, const int qt, unsigned char* smem) {
;     ...
;         const bf16_t* SU = (const bf16_t*)(p.ws + (MODE == 0 ? W_SUA : W_SUB));
;         bf16_t* OAB = (bf16_t*)(p.ws + W_OAB);
; #pragma unroll
;         for (int j = 0; j < 2; ++j) {
;             float inv = 1.0f;
;             if (MODE == 0) { float l = st_l[j]; l += shx(l, 16); l += shx(l, 32); inv = (l > 0.f) ? __builtin_amdgcn_rcpf(l) : 0.f; }
;             const int tok = tok0 + 16 * j + l15;
; #pragma unroll
;             for (int dt = 0; dt < 4; ++dt) {
;                 const int col = h * 64 + 16 * dt + 4 * g;
;                 const u32x2 su = *(const u32x2*)(SU + (size_t)tok * 512 + col);
;                 f32x4 o = O[dt][j] * inv;
;                 u32x2 ov; ov.x = pk_bf16(o[0] * bf_lo(su.x), o[1] * bf_hi(su.x)); ov.y = pk_bf16(o[2] * bf_lo(su.y), o[3] * bf_hi(su.y));
;                 *(u32x2*)(OAB + (MODE == 0 ? (size_t)0 : (size_t)NTOK * 512) + (size_t)tok * 512 + col) = ov;
;             }
.LBB0_758:
	s_or_b64 exec, exec, s[58:59]
	v_or_b32_e32 v0, s73, v158
	v_lshl_add_u64 v[2:3], s[52:53], 0, v[70:71]
	v_lshlrev_b32_e32 v0, 1, v0
	v_lshl_add_u64 v[2:3], v[2:3], 0, v[0:1]
	global_load_dwordx2 v[8:9], v[2:3], off
	global_load_dwordx2 v[10:11], v[2:3], off offset:32
	global_load_dwordx2 v[12:13], v[2:3], off offset:64
	s_nop 0
	global_load_dwordx2 v[2:3], v[2:3], off offset:96
	v_lshl_add_u64 v[14:15], s[52:53], 0, v[72:73]
	v_lshl_add_u64 v[14:15], v[14:15], 0, v[0:1]
	global_load_dwordx2 v[16:17], v[14:15], off
	global_load_dwordx2 v[18:19], v[14:15], off offset:32
	global_load_dwordx2 v[20:21], v[14:15], off offset:64
	s_nop 0
	global_load_dwordx2 v[14:15], v[14:15], off offset:96
	v_lshl_add_u64 v[22:23], s[54:55], 0, v[70:71]
	v_lshl_add_u64 v[52:53], s[54:55], 0, v[72:73]
	v_lshl_add_u64 v[22:23], v[22:23], 0, v[0:1]
	s_add_u32 s0, s56, 0xc0
	v_lshl_add_u64 v[52:53], v[52:53], 0, v[0:1]
	s_addc_u32 s1, s57, 0
	s_addk_i32 s70, 0x300
	s_cmpk_gt_i32 s56, 0x33f
	s_mov_b64 s[56:57], s[0:1]
	s_waitcnt vmcnt(7)
	v_lshlrev_b32_e32 v54, 16, v8
	v_and_b32_e32 v55, 0xffff0000, v8
	v_lshlrev_b32_e32 v8, 16, v9
	v_and_b32_e32 v9, 0xffff0000, v9
	s_waitcnt vmcnt(6)
	v_lshlrev_b32_e32 v56, 16, v10
	v_and_b32_e32 v57, 0xffff0000, v10
	v_lshlrev_b32_e32 v10, 16, v11
	v_and_b32_e32 v11, 0xffff0000, v11
	s_waitcnt vmcnt(5)
	v_lshlrev_b32_e32 v58, 16, v12
	v_and_b32_e32 v59, 0xffff0000, v12
	v_lshlrev_b32_e32 v12, 16, v13
	v_and_b32_e32 v13, 0xffff0000, v13
	s_waitcnt vmcnt(4)
	v_lshlrev_b32_e32 v60, 16, v2
	v_and_b32_e32 v61, 0xffff0000, v2
	v_lshlrev_b32_e32 v2, 16, v3
	v_and_b32_e32 v3, 0xffff0000, v3
	s_waitcnt vmcnt(3)
	v_lshlrev_b32_e32 v62, 16, v16
	v_and_b32_e32 v63, 0xffff0000, v16
	v_lshlrev_b32_e32 v16, 16, v17
	v_and_b32_e32 v17, 0xffff0000, v17
	s_waitcnt vmcnt(2)
	v_lshlrev_b32_e32 v64, 16, v18
	v_and_b32_e32 v65, 0xffff0000, v18
	v_lshlrev_b32_e32 v18, 16, v19
	v_and_b32_e32 v19, 0xffff0000, v19
	s_waitcnt vmcnt(1)
	v_lshlrev_b32_e32 v66, 16, v20
	v_and_b32_e32 v67, 0xffff0000, v20
	v_lshlrev_b32_e32 v20, 16, v21
	v_and_b32_e32 v21, 0xffff0000, v21
	v_pk_mul_f32 v[48:49], v[48:49], v[54:55]
	v_pk_mul_f32 v[8:9], v[50:51], v[8:9]
	v_pk_mul_f32 v[10:11], v[42:43], v[10:11]
	v_pk_mul_f32 v[12:13], v[38:39], v[12:13]
	v_pk_mul_f32 v[2:3], v[34:35], v[2:3]
	v_pk_mul_f32 v[34:35], v[44:45], v[62:63]
	v_pk_mul_f32 v[16:17], v[46:47], v[16:17]
	s_waitcnt vmcnt(0)
	v_lshlrev_b32_e32 v70, 16, v14
	v_and_b32_e32 v71, 0xffff0000, v14
	v_lshlrev_b32_e32 v14, 16, v15
	v_and_b32_e32 v15, 0xffff0000, v15
	v_pk_mul_f32 v[40:41], v[40:41], v[56:57]
	v_pk_mul_f32 v[36:37], v[36:37], v[58:59]
	v_pk_mul_f32 v[32:33], v[32:33], v[60:61]
	v_pk_mul_f32 v[28:29], v[28:29], v[64:65]
	v_pk_mul_f32 v[18:19], v[30:31], v[18:19]
	v_pk_mul_f32 v[24:25], v[24:25], v[66:67]
	v_pk_mul_f32 v[20:21], v[26:27], v[20:21]
	v_cvt_pk_bf16_f32 v26, v48, v49
	v_cvt_pk_bf16_f32 v27, v8, v9
	v_cvt_pk_bf16_f32 v9, v10, v11
	v_cvt_pk_bf16_f32 v11, v12, v13
	v_cvt_pk_bf16_f32 v13, v2, v3
	v_cvt_pk_bf16_f32 v2, v34, v35
	v_cvt_pk_bf16_f32 v3, v16, v17
	v_pk_mul_f32 v[4:5], v[4:5], v[70:71]
	v_cvt_pk_bf16_f32 v8, v40, v41
	v_cvt_pk_bf16_f32 v10, v36, v37
	v_cvt_pk_bf16_f32 v12, v32, v33
	v_cvt_pk_bf16_f32 v16, v28, v29
	v_cvt_pk_bf16_f32 v17, v18, v19
	v_cvt_pk_bf16_f32 v18, v24, v25
	v_cvt_pk_bf16_f32 v19, v20, v21
	v_and_b32_e32 v250, 63, v203
	v_and_b32_e32 v251, 3, v250
	v_lshrrev_b32_e32 v252, 4, v250
	v_bfe_u32 v253, v250, 2, 2
	v_lshl_add_u32 v252, v252, 2, v253
	v_lshl_add_u32 v250, v251, 4, v252
	v_lshlrev_b32_e32 v250, 2, v250
	ds_bpermute_b32 v246, v250, v22
	ds_bpermute_b32 v247, v250, v23
	ds_bpermute_b32 v248, v250, v26
	ds_bpermute_b32 v249, v250, v27
	s_waitcnt lgkmcnt(0)
	global_store_dwordx2 v[246:247], v[248:249], off
	ds_bpermute_b32 v246, v250, v22
	ds_bpermute_b32 v247, v250, v23
	ds_bpermute_b32 v248, v250, v8
	ds_bpermute_b32 v249, v250, v9
	s_waitcnt lgkmcnt(0)
	global_store_dwordx2 v[246:247], v[248:249], off offset:32
	ds_bpermute_b32 v246, v250, v22
	ds_bpermute_b32 v247, v250, v23
	ds_bpermute_b32 v248, v250, v10
	ds_bpermute_b32 v249, v250, v11
	s_waitcnt lgkmcnt(0)
	global_store_dwordx2 v[246:247], v[248:249], off offset:64
	ds_bpermute_b32 v246, v250, v22
	ds_bpermute_b32 v247, v250, v23
	ds_bpermute_b32 v248, v250, v12
	ds_bpermute_b32 v249, v250, v13
	s_waitcnt lgkmcnt(0)
	global_store_dwordx2 v[246:247], v[248:249], off offset:96
	ds_bpermute_b32 v246, v250, v52
	ds_bpermute_b32 v247, v250, v53
	ds_bpermute_b32 v248, v250, v2
	ds_bpermute_b32 v249, v250, v3
	s_waitcnt lgkmcnt(0)
	global_store_dwordx2 v[246:247], v[248:249], off
	ds_bpermute_b32 v246, v250, v52
	ds_bpermute_b32 v247, v250, v53
	ds_bpermute_b32 v248, v250, v16
	ds_bpermute_b32 v249, v250, v17
	s_waitcnt lgkmcnt(0)
	global_store_dwordx2 v[246:247], v[248:249], off offset:32
	ds_bpermute_b32 v246, v250, v52
	ds_bpermute_b32 v247, v250, v53
	ds_bpermute_b32 v248, v250, v18
	ds_bpermute_b32 v249, v250, v19
	s_waitcnt lgkmcnt(0)
	global_store_dwordx2 v[246:247], v[248:249], off offset:64
	v_pk_mul_f32 v[2:3], v[6:7], v[14:15]
	v_cvt_pk_bf16_f32 v4, v4, v5
	v_cvt_pk_bf16_f32 v5, v2, v3
	ds_bpermute_b32 v246, v250, v52
	ds_bpermute_b32 v247, v250, v53
	ds_bpermute_b32 v248, v250, v4
	ds_bpermute_b32 v249, v250, v5
	s_waitcnt lgkmcnt(0)
	global_store_dwordx2 v[246:247], v[248:249], off offset:96
	s_barrier
	s_cbranch_scc1 .LBB0_781

; DEVI unsigned pk_bf16(float lo, float hi) { const f32x2_t v = {lo, hi}; const bf16x2_t b = __builtin_convertvector(v, bf16x2_t); return __builtin_bit_cast(unsigned, b); }
; DEVI float bf_lo(unsigned u) { return __uint_as_float(u << 16); }
; DEVI float bf_hi(unsigned u) { return __uint_as_float(u & 0xffff0000u); }
; DEVI float shx(float v, int m) { return __shfl_xor(v, m); }
; template <int MODE, bool SAMPLE>
; DEVI void attn_unit(const Params& p, const int b, const int h, const int qt, unsigned char* smem) {
;     ...
;         const bf16_t* SU = (const bf16_t*)(p.ws + (MODE == 0 ? W_SUA : W_SUB));
;         bf16_t* OAB = (bf16_t*)(p.ws + W_OAB);
; #pragma unroll
;         for (int j = 0; j < 2; ++j) {
;             float inv = 1.0f;
;             if (MODE == 0) { float l = st_l[j]; l += shx(l, 16); l += shx(l, 32); inv = (l > 0.f) ? __builtin_amdgcn_rcpf(l) : 0.f; }
;             const int tok = tok0 + 16 * j + l15;
; #pragma unroll
;             for (int dt = 0; dt < 4; ++dt) {
;                 const int col = h * 64 + 16 * dt + 4 * g;
;                 const u32x2 su = *(const u32x2*)(SU + (size_t)tok * 512 + col);
;                 f32x4 o = O[dt][j] * inv;
;                 u32x2 ov; ov.x = pk_bf16(o[0] * bf_lo(su.x), o[1] * bf_hi(su.x)); ov.y = pk_bf16(o[2] * bf_lo(su.y), o[3] * bf_hi(su.y));
;                 *(u32x2*)(OAB + (MODE == 0 ? (size_t)0 : (size_t)NTOK * 512) + (size_t)tok * 512 + col) = ov;
;             }
.LBB0_784:
	s_or_b64 exec, exec, s[54:55]
	v_or_b32_e32 v0, s66, v158
	v_lshl_add_u64 v[2:3], s[50:51], 0, v[70:71]
	v_lshlrev_b32_e32 v0, 1, v0
	v_lshl_add_u64 v[2:3], v[2:3], 0, v[0:1]
	global_load_dwordx2 v[8:9], v[2:3], off
	global_load_dwordx2 v[10:11], v[2:3], off offset:32
	global_load_dwordx2 v[12:13], v[2:3], off offset:64
	s_nop 0
	global_load_dwordx2 v[2:3], v[2:3], off offset:96
	v_lshl_add_u64 v[14:15], s[50:51], 0, v[72:73]
	v_lshl_add_u64 v[14:15], v[14:15], 0, v[0:1]
	global_load_dwordx2 v[16:17], v[14:15], off
	global_load_dwordx2 v[18:19], v[14:15], off offset:32
	global_load_dwordx2 v[20:21], v[14:15], off offset:64
	s_nop 0
	global_load_dwordx2 v[14:15], v[14:15], off offset:96
	v_lshl_add_u64 v[22:23], s[52:53], 0, v[70:71]
	v_lshl_add_u64 v[52:53], s[52:53], 0, v[72:73]
	v_lshl_add_u64 v[22:23], v[22:23], 0, v[0:1]
	v_lshl_add_u64 v[52:53], v[52:53], 0, v[0:1]
	s_add_i32 s0, s60, 1
	s_add_i32 s93, s93, 4
	s_cmp_eq_u32 s60, s2
	s_mov_b32 s60, s0
	s_waitcnt vmcnt(7)
	v_lshlrev_b32_e32 v54, 16, v8
	v_and_b32_e32 v55, 0xffff0000, v8
	v_lshlrev_b32_e32 v8, 16, v9
	v_and_b32_e32 v9, 0xffff0000, v9
	s_waitcnt vmcnt(6)
	v_lshlrev_b32_e32 v56, 16, v10
	v_and_b32_e32 v57, 0xffff0000, v10
	v_lshlrev_b32_e32 v10, 16, v11
	v_and_b32_e32 v11, 0xffff0000, v11
	s_waitcnt vmcnt(5)
	v_lshlrev_b32_e32 v58, 16, v12
	v_and_b32_e32 v59, 0xffff0000, v12
	v_lshlrev_b32_e32 v12, 16, v13
	v_and_b32_e32 v13, 0xffff0000, v13
	s_waitcnt vmcnt(4)
	v_lshlrev_b32_e32 v60, 16, v2
	v_and_b32_e32 v61, 0xffff0000, v2
	v_lshlrev_b32_e32 v2, 16, v3
	v_and_b32_e32 v3, 0xffff0000, v3
	s_waitcnt vmcnt(3)
	v_lshlrev_b32_e32 v62, 16, v16
	v_and_b32_e32 v63, 0xffff0000, v16
	v_lshlrev_b32_e32 v16, 16, v17
	v_and_b32_e32 v17, 0xffff0000, v17
	s_waitcnt vmcnt(2)
	v_lshlrev_b32_e32 v64, 16, v18
	v_and_b32_e32 v65, 0xffff0000, v18
	v_lshlrev_b32_e32 v18, 16, v19
	v_and_b32_e32 v19, 0xffff0000, v19
	s_waitcnt vmcnt(1)
	v_lshlrev_b32_e32 v66, 16, v20
	v_and_b32_e32 v67, 0xffff0000, v20
	v_lshlrev_b32_e32 v20, 16, v21
	v_and_b32_e32 v21, 0xffff0000, v21
	v_pk_mul_f32 v[48:49], v[48:49], v[54:55]
	v_pk_mul_f32 v[8:9], v[50:51], v[8:9]
	v_pk_mul_f32 v[10:11], v[42:43], v[10:11]
	v_pk_mul_f32 v[12:13], v[38:39], v[12:13]
	v_pk_mul_f32 v[2:3], v[34:35], v[2:3]
	v_pk_mul_f32 v[34:35], v[44:45], v[62:63]
	v_pk_mul_f32 v[16:17], v[46:47], v[16:17]
	s_waitcnt vmcnt(0)
	v_lshlrev_b32_e32 v70, 16, v14
	v_and_b32_e32 v71, 0xffff0000, v14
	v_lshlrev_b32_e32 v14, 16, v15
	v_and_b32_e32 v15, 0xffff0000, v15
	v_pk_mul_f32 v[40:41], v[40:41], v[56:57]
	v_pk_mul_f32 v[36:37], v[36:37], v[58:59]
	v_pk_mul_f32 v[32:33], v[32:33], v[60:61]
	v_pk_mul_f32 v[28:29], v[28:29], v[64:65]
	v_pk_mul_f32 v[18:19], v[30:31], v[18:19]
	v_pk_mul_f32 v[24:25], v[24:25], v[66:67]
	v_pk_mul_f32 v[20:21], v[26:27], v[20:21]
	v_cvt_pk_bf16_f32 v26, v48, v49
	v_cvt_pk_bf16_f32 v27, v8, v9
	v_cvt_pk_bf16_f32 v9, v10, v11
	v_cvt_pk_bf16_f32 v11, v12, v13
	v_cvt_pk_bf16_f32 v13, v2, v3
	v_cvt_pk_bf16_f32 v2, v34, v35
	v_cvt_pk_bf16_f32 v3, v16, v17
	v_pk_mul_f32 v[4:5], v[4:5], v[70:71]
	v_cvt_pk_bf16_f32 v8, v40, v41
	v_cvt_pk_bf16_f32 v10, v36, v37
	v_cvt_pk_bf16_f32 v12, v32, v33
	v_cvt_pk_bf16_f32 v16, v28, v29
	v_cvt_pk_bf16_f32 v17, v18, v19
	v_cvt_pk_bf16_f32 v18, v24, v25
	v_cvt_pk_bf16_f32 v19, v20, v21
	v_and_b32_e32 v250, 63, v203
	v_and_b32_e32 v251, 3, v250
	v_lshrrev_b32_e32 v252, 4, v250
	v_bfe_u32 v253, v250, 2, 2
	v_lshl_add_u32 v252, v252, 2, v253
	v_lshl_add_u32 v250, v251, 4, v252
	v_lshlrev_b32_e32 v250, 2, v250
	ds_bpermute_b32 v246, v250, v22
	ds_bpermute_b32 v247, v250, v23
	ds_bpermute_b32 v248, v250, v26
	ds_bpermute_b32 v249, v250, v27
	s_waitcnt lgkmcnt(0)
	global_store_dwordx2 v[246:247], v[248:249], off
	ds_bpermute_b32 v246, v250, v22
	ds_bpermute_b32 v247, v250, v23
	ds_bpermute_b32 v248, v250, v8
	ds_bpermute_b32 v249, v250, v9
	s_waitcnt lgkmcnt(0)
	global_store_dwordx2 v[246:247], v[248:249], off offset:32
	ds_bpermute_b32 v246, v250, v22
	ds_bpermute_b32 v247, v250, v23
	ds_bpermute_b32 v248, v250, v10
	ds_bpermute_b32 v249, v250, v11
	s_waitcnt lgkmcnt(0)
	global_store_dwordx2 v[246:247], v[248:249], off offset:64
	ds_bpermute_b32 v246, v250, v22
	ds_bpermute_b32 v247, v250, v23
	ds_bpermute_b32 v248, v250, v12
	ds_bpermute_b32 v249, v250, v13
	s_waitcnt lgkmcnt(0)
	global_store_dwordx2 v[246:247], v[248:249], off offset:96
	ds_bpermute_b32 v246, v250, v52
	ds_bpermute_b32 v247, v250, v53
	ds_bpermute_b32 v248, v250, v2
	ds_bpermute_b32 v249, v250, v3
	s_waitcnt lgkmcnt(0)
	global_store_dwordx2 v[246:247], v[248:249], off
	ds_bpermute_b32 v246, v250, v52
	ds_bpermute_b32 v247, v250, v53
	ds_bpermute_b32 v248, v250, v16
	ds_bpermute_b32 v249, v250, v17
	s_waitcnt lgkmcnt(0)
	global_store_dwordx2 v[246:247], v[248:249], off offset:32
	ds_bpermute_b32 v246, v250, v52
	ds_bpermute_b32 v247, v250, v53
	ds_bpermute_b32 v248, v250, v18
	ds_bpermute_b32 v249, v250, v19
	s_waitcnt lgkmcnt(0)
	global_store_dwordx2 v[246:247], v[248:249], off offset:64
	v_pk_mul_f32 v[2:3], v[6:7], v[14:15]
	v_cvt_pk_bf16_f32 v4, v4, v5
	v_cvt_pk_bf16_f32 v5, v2, v3
	ds_bpermute_b32 v246, v250, v52
	ds_bpermute_b32 v247, v250, v53
	ds_bpermute_b32 v248, v250, v4
	ds_bpermute_b32 v249, v250, v5
	s_waitcnt lgkmcnt(0)
	global_store_dwordx2 v[246:247], v[248:249], off offset:96
	s_barrier
	s_cbranch_scc1 .LBB0_807

; DEVI unsigned pk_bf16(float lo, float hi) { const f32x2_t v = {lo, hi}; const bf16x2_t b = __builtin_convertvector(v, bf16x2_t); return __builtin_bit_cast(unsigned, b); }
; DEVI float bf_lo(unsigned u) { return __uint_as_float(u << 16); }
; DEVI float bf_hi(unsigned u) { return __uint_as_float(u & 0xffff0000u); }
; DEVI float shx(float v, int m) { return __shfl_xor(v, m); }
; template <int MODE, bool SAMPLE>
; DEVI void attn_unit(const Params& p, const int b, const int h, const int qt, unsigned char* smem) {
;     ...
;     if (active) {
;         const bf16_t* SU = (const bf16_t*)(p.ws + (MODE == 0 ? W_SUA : W_SUB));
;         bf16_t* OAB = (bf16_t*)(p.ws + W_OAB);
; #pragma unroll
;         for (int j = 0; j < 2; ++j) {
;             float inv = 1.0f;
;             if (MODE == 0) { float l = st_l[j]; l += shx(l, 16); l += shx(l, 32); inv = (l > 0.f) ? __builtin_amdgcn_rcpf(l) : 0.f; }
;             const int tok = tok0 + 16 * j + l15;
; #pragma unroll
;             for (int dt = 0; dt < 4; ++dt) {
;                 const int col = h * 64 + 16 * dt + 4 * g;
;                 const u32x2 su = *(const u32x2*)(SU + (size_t)tok * 512 + col);
;                 f32x4 o = O[dt][j] * inv;
;                 u32x2 ov; ov.x = pk_bf16(o[0] * bf_lo(su.x), o[1] * bf_hi(su.x)); ov.y = pk_bf16(o[2] * bf_lo(su.y), o[3] * bf_hi(su.y));
;                 *(u32x2*)(OAB + (MODE == 0 ? (size_t)0 : (size_t)NTOK * 512) + (size_t)tok * 512 + col) = ov;
;             }
.LBB0_833:
	s_or_b64 exec, exec, s[18:19]
	s_and_saveexec_b64 s[0:1], s[12:13]
	s_cbranch_execz .LBB0_809
	v_or_b32_e32 v2, s43, v118
	v_lshl_add_u64 v[0:1], s[24:25], 0, v[68:69]
	v_lshlrev_b32_e32 v64, 1, v2
	v_lshl_add_u64 v[0:1], v[0:1], 0, v[64:65]
	global_load_dwordx2 v[2:3], v[0:1], off
	global_load_dwordx2 v[4:5], v[0:1], off offset:32
	global_load_dwordx2 v[6:7], v[0:1], off offset:64
	s_nop 0
	global_load_dwordx2 v[0:1], v[0:1], off offset:96
	v_lshl_add_u64 v[8:9], s[24:25], 0, v[70:71]
	v_lshl_add_u64 v[8:9], v[8:9], 0, v[64:65]
	global_load_dwordx2 v[10:11], v[8:9], off
	global_load_dwordx2 v[12:13], v[8:9], off offset:32
	global_load_dwordx2 v[14:15], v[8:9], off offset:64
	s_nop 0
	global_load_dwordx2 v[8:9], v[8:9], off offset:96
	v_lshl_add_u64 v[48:49], s[26:27], 0, v[68:69]
	v_lshl_add_u64 v[50:51], s[26:27], 0, v[70:71]
	v_lshl_add_u64 v[48:49], v[48:49], 0, v[64:65]
	v_lshl_add_u64 v[50:51], v[50:51], 0, v[64:65]
	s_waitcnt vmcnt(7)
	v_lshlrev_b32_e32 v52, 16, v2
	v_and_b32_e32 v53, 0xffff0000, v2
	v_lshlrev_b32_e32 v2, 16, v3
	v_and_b32_e32 v3, 0xffff0000, v3
	s_waitcnt vmcnt(6)
	v_lshlrev_b32_e32 v54, 16, v4
	v_and_b32_e32 v55, 0xffff0000, v4
	v_lshlrev_b32_e32 v4, 16, v5
	v_and_b32_e32 v5, 0xffff0000, v5
	s_waitcnt vmcnt(5)
	v_lshlrev_b32_e32 v56, 16, v6
	v_and_b32_e32 v57, 0xffff0000, v6
	v_lshlrev_b32_e32 v6, 16, v7
	v_and_b32_e32 v7, 0xffff0000, v7
	s_waitcnt vmcnt(4)
	v_lshlrev_b32_e32 v58, 16, v0
	v_and_b32_e32 v59, 0xffff0000, v0
	v_lshlrev_b32_e32 v0, 16, v1
	v_and_b32_e32 v1, 0xffff0000, v1
	s_waitcnt vmcnt(3)
	v_lshlrev_b32_e32 v60, 16, v10
	v_and_b32_e32 v61, 0xffff0000, v10
	v_lshlrev_b32_e32 v10, 16, v11
	v_and_b32_e32 v11, 0xffff0000, v11
	s_waitcnt vmcnt(2)
	v_lshlrev_b32_e32 v62, 16, v12
	v_and_b32_e32 v63, 0xffff0000, v12
	v_lshlrev_b32_e32 v12, 16, v13
	v_and_b32_e32 v13, 0xffff0000, v13
	s_waitcnt vmcnt(1)
	v_lshlrev_b32_e32 v68, 16, v14
	v_and_b32_e32 v69, 0xffff0000, v14
	v_lshlrev_b32_e32 v14, 16, v15
	v_and_b32_e32 v15, 0xffff0000, v15
	v_pk_mul_f32 v[24:25], v[24:25], v[52:53]
	v_pk_mul_f32 v[2:3], v[26:27], v[2:3]
	v_pk_mul_f32 v[4:5], v[34:35], v[4:5]
	v_pk_mul_f32 v[6:7], v[42:43], v[6:7]
	v_pk_mul_f32 v[0:1], v[46:47], v[0:1]
	v_pk_mul_f32 v[16:17], v[16:17], v[60:61]
	v_pk_mul_f32 v[10:11], v[18:19], v[10:11]
	s_waitcnt vmcnt(0)
	v_lshlrev_b32_e32 v70, 16, v8
	v_and_b32_e32 v71, 0xffff0000, v8
	v_lshlrev_b32_e32 v8, 16, v9
	v_and_b32_e32 v9, 0xffff0000, v9
	v_pk_mul_f32 v[26:27], v[32:33], v[54:55]
	v_pk_mul_f32 v[32:33], v[40:41], v[56:57]
	v_pk_mul_f32 v[34:35], v[44:45], v[58:59]
	v_pk_mul_f32 v[18:19], v[28:29], v[62:63]
	v_pk_mul_f32 v[12:13], v[30:31], v[12:13]
	v_pk_mul_f32 v[28:29], v[36:37], v[68:69]
	v_pk_mul_f32 v[14:15], v[38:39], v[14:15]
	v_cvt_pk_bf16_f32 v24, v24, v25
	v_cvt_pk_bf16_f32 v25, v2, v3
	v_cvt_pk_bf16_f32 v3, v4, v5
	v_cvt_pk_bf16_f32 v5, v6, v7
	v_cvt_pk_bf16_f32 v7, v0, v1
	v_cvt_pk_bf16_f32 v0, v16, v17
	v_cvt_pk_bf16_f32 v1, v10, v11
	v_pk_mul_f32 v[20:21], v[20:21], v[70:71]
	v_cvt_pk_bf16_f32 v2, v26, v27
	v_cvt_pk_bf16_f32 v4, v32, v33
	v_cvt_pk_bf16_f32 v6, v34, v35
	v_cvt_pk_bf16_f32 v10, v18, v19
	v_cvt_pk_bf16_f32 v11, v12, v13
	v_cvt_pk_bf16_f32 v12, v28, v29
	v_cvt_pk_bf16_f32 v13, v14, v15
	v_and_b32_e32 v250, 63, v203
	v_and_b32_e32 v251, 3, v250
	v_lshrrev_b32_e32 v252, 4, v250
	v_bfe_u32 v253, v250, 2, 2
	v_lshl_add_u32 v252, v252, 2, v253
	v_lshl_add_u32 v250, v251, 4, v252
	v_lshlrev_b32_e32 v250, 2, v250
	ds_bpermute_b32 v246, v250, v48
	ds_bpermute_b32 v247, v250, v49
	ds_bpermute_b32 v248, v250, v24
	ds_bpermute_b32 v249, v250, v25
	s_waitcnt lgkmcnt(0)
	global_store_dwordx2 v[246:247], v[248:249], off
	ds_bpermute_b32 v246, v250, v48
	ds_bpermute_b32 v247, v250, v49
	ds_bpermute_b32 v248, v250, v2
	ds_bpermute_b32 v249, v250, v3
	s_waitcnt lgkmcnt(0)
	global_store_dwordx2 v[246:247], v[248:249], off offset:32
	ds_bpermute_b32 v246, v250, v48
	ds_bpermute_b32 v247, v250, v49
	ds_bpermute_b32 v248, v250, v4
	ds_bpermute_b32 v249, v250, v5
	s_waitcnt lgkmcnt(0)
	global_store_dwordx2 v[246:247], v[248:249], off offset:64
	ds_bpermute_b32 v246, v250, v48
	ds_bpermute_b32 v247, v250, v49
	ds_bpermute_b32 v248, v250, v6
	ds_bpermute_b32 v249, v250, v7
	s_waitcnt lgkmcnt(0)
	global_store_dwordx2 v[246:247], v[248:249], off offset:96
	ds_bpermute_b32 v246, v250, v50
	ds_bpermute_b32 v247, v250, v51
	ds_bpermute_b32 v248, v250, v0
	ds_bpermute_b32 v249, v250, v1
	s_waitcnt lgkmcnt(0)
	global_store_dwordx2 v[246:247], v[248:249], off
	ds_bpermute_b32 v246, v250, v50
	ds_bpermute_b32 v247, v250, v51
	ds_bpermute_b32 v248, v250, v10
	ds_bpermute_b32 v249, v250, v11
	s_waitcnt lgkmcnt(0)
	global_store_dwordx2 v[246:247], v[248:249], off offset:32
	ds_bpermute_b32 v246, v250, v50
	ds_bpermute_b32 v247, v250, v51
	ds_bpermute_b32 v248, v250, v12
	ds_bpermute_b32 v249, v250, v13
	s_waitcnt lgkmcnt(0)
	global_store_dwordx2 v[246:247], v[248:249], off offset:64
	v_pk_mul_f32 v[0:1], v[22:23], v[8:9]
	v_cvt_pk_bf16_f32 v14, v20, v21
	v_cvt_pk_bf16_f32 v15, v0, v1
	ds_bpermute_b32 v246, v250, v50
	ds_bpermute_b32 v247, v250, v51
	ds_bpermute_b32 v248, v250, v14
	ds_bpermute_b32 v249, v250, v15
	s_waitcnt lgkmcnt(0)
	global_store_dwordx2 v[246:247], v[248:249], off offset:96
	s_branch .LBB0_809

; DEVI unsigned pk_bf16(float lo, float hi) { const f32x2_t v = {lo, hi}; const bf16x2_t b = __builtin_convertvector(v, bf16x2_t); return __builtin_bit_cast(unsigned, b); }
; DEVI float bf_lo(unsigned u) { return __uint_as_float(u << 16); }
; DEVI float bf_hi(unsigned u) { return __uint_as_float(u & 0xffff0000u); }
; DEVI float shx(float v, int m) { return __shfl_xor(v, m); }
; template <int MODE, bool SAMPLE>
; DEVI void attn_unit(const Params& p, const int b, const int h, const int qt, unsigned char* smem) {
;     ...
; #pragma unroll
;         for (int j = 0; j < 2; ++j) {
;             float inv = 1.0f;
;             if (MODE == 0) { float l = st_l[j]; l += shx(l, 16); l += shx(l, 32); inv = (l > 0.f) ? __builtin_amdgcn_rcpf(l) : 0.f; }
;             const int tok = tok0 + 16 * j + l15;
; #pragma unroll
;             for (int dt = 0; dt < 4; ++dt) {
;                 const int col = h * 64 + 16 * dt + 4 * g;
;                 const u32x2 su = *(const u32x2*)(SU + (size_t)tok * 512 + col);
;                 f32x4 o = O[dt][j] * inv;
;                 u32x2 ov; ov.x = pk_bf16(o[0] * bf_lo(su.x), o[1] * bf_hi(su.x)); ov.y = pk_bf16(o[2] * bf_lo(su.y), o[3] * bf_hi(su.y));
;                 *(u32x2*)(OAB + (MODE == 0 ? (size_t)0 : (size_t)NTOK * 512) + (size_t)tok * 512 + col) = ov;
;             }
.LBB0_892:
	s_or_b64 exec, exec, s[4:5]
	v_or_b32_e32 v36, s60, v73
	v_lshlrev_b64 v[32:33], 1, v[62:63]
	v_lshl_add_u64 v[34:35], s[14:15], 0, v[32:33]
	v_lshlrev_b32_e32 v64, 1, v36
	v_lshl_add_u64 v[34:35], v[34:35], 0, v[64:65]
	v_lshlrev_b64 v[42:43], 1, v[60:61]
	s_barrier
	global_load_dwordx2 v[36:37], v[34:35], off
	global_load_dwordx2 v[38:39], v[34:35], off offset:32
	global_load_dwordx2 v[40:41], v[34:35], off offset:64
	s_nop 0
	global_load_dwordx2 v[34:35], v[34:35], off offset:96
	v_lshl_add_u64 v[44:45], s[14:15], 0, v[42:43]
	v_cmp_lt_i32_e32 vcc, v49, v48
	v_lshl_add_u64 v[44:45], v[44:45], 0, v[64:65]
	global_load_dwordx2 v[46:47], v[44:45], off
	global_load_dwordx2 v[52:53], v[44:45], off offset:32
	v_cndmask_b32_e32 v49, v51, v49, vcc
	v_lshlrev_b32_e32 v98, 2, v49
	ds_bpermute_b32 v54, v98, v68
	ds_bpermute_b32 v55, v98, v69
	v_cmp_lt_i32_e32 vcc, v50, v48
	v_lshl_add_u64 v[32:33], s[16:17], 0, v[32:33]
	v_lshl_add_u64 v[32:33], v[32:33], 0, v[64:65]
	v_cndmask_b32_e32 v48, v51, v50, vcc
	v_lshlrev_b32_e32 v99, 2, v48
	s_waitcnt lgkmcnt(0)
	v_pk_add_f32 v[48:49], v[68:69], v[54:55]
	global_load_dwordx2 v[54:55], v[44:45], off offset:64
	ds_bpermute_b32 v50, v99, v48
	global_load_dwordx2 v[44:45], v[44:45], off offset:96
	ds_bpermute_b32 v51, v99, v49
	v_lshl_add_u64 v[42:43], s[16:17], 0, v[42:43]
	s_add_i32 s61, s61, 1
	s_cmp_eq_u32 s61, 4
	s_waitcnt lgkmcnt(0)
	v_pk_add_f32 v[48:49], v[48:49], v[50:51]
	s_nop 0
	v_rcp_f32_e32 v50, v48
	v_rcp_f32_e32 v51, v49
	v_cmp_lt_f32_e32 vcc, 0, v48
	s_waitcnt vmcnt(6)
	v_lshlrev_b32_e32 v56, 16, v38
	v_cndmask_b32_e32 v48, 0, v50, vcc
	v_cmp_lt_f32_e32 vcc, 0, v49
	v_pk_mul_f32 v[30:31], v[30:31], v[48:49] op_sel_hi:[1,0]
	v_pk_mul_f32 v[28:29], v[28:29], v[48:49] op_sel_hi:[1,0]
	v_pk_mul_f32 v[14:15], v[14:15], v[48:49] op_sel_hi:[1,0]
	v_pk_mul_f32 v[12:13], v[12:13], v[48:49] op_sel_hi:[1,0]
	v_pk_mul_f32 v[26:27], v[26:27], v[48:49] op_sel_hi:[1,0]
	v_pk_mul_f32 v[24:25], v[24:25], v[48:49] op_sel_hi:[1,0]
	v_pk_mul_f32 v[18:19], v[18:19], v[48:49] op_sel_hi:[1,0]
	v_pk_mul_f32 v[16:17], v[16:17], v[48:49] op_sel_hi:[1,0]
	v_lshlrev_b32_e32 v48, 16, v36
	v_and_b32_e32 v49, 0xffff0000, v36
	v_lshlrev_b32_e32 v36, 16, v37
	v_and_b32_e32 v37, 0xffff0000, v37
	v_and_b32_e32 v57, 0xffff0000, v38
	v_lshlrev_b32_e32 v38, 16, v39
	v_and_b32_e32 v39, 0xffff0000, v39
	s_waitcnt vmcnt(5)
	v_lshlrev_b32_e32 v58, 16, v40
	v_and_b32_e32 v59, 0xffff0000, v40
	v_lshlrev_b32_e32 v40, 16, v41
	v_and_b32_e32 v41, 0xffff0000, v41
	s_waitcnt vmcnt(4)
	v_lshlrev_b32_e32 v60, 16, v34
	v_and_b32_e32 v61, 0xffff0000, v34
	v_lshlrev_b32_e32 v34, 16, v35
	v_and_b32_e32 v35, 0xffff0000, v35
	v_pk_mul_f32 v[28:29], v[28:29], v[48:49]
	v_pk_mul_f32 v[30:31], v[30:31], v[36:37]
	v_pk_mul_f32 v[12:13], v[12:13], v[56:57]
	v_pk_mul_f32 v[14:15], v[14:15], v[38:39]
	v_pk_mul_f32 v[24:25], v[24:25], v[58:59]
	v_pk_mul_f32 v[26:27], v[26:27], v[40:41]
	v_cndmask_b32_e32 v50, 0, v51, vcc
	v_pk_mul_f32 v[16:17], v[16:17], v[60:61]
	v_pk_mul_f32 v[18:19], v[18:19], v[34:35]
	v_cvt_pk_bf16_f32 v28, v28, v29
	v_cvt_pk_bf16_f32 v29, v30, v31
	v_cvt_pk_bf16_f32 v12, v12, v13
	v_cvt_pk_bf16_f32 v13, v14, v15
	v_cvt_pk_bf16_f32 v14, v24, v25
	v_cvt_pk_bf16_f32 v15, v26, v27
	v_pk_mul_f32 v[22:23], v[22:23], v[50:51] op_sel_hi:[1,0]
	v_pk_mul_f32 v[20:21], v[20:21], v[50:51] op_sel_hi:[1,0]
	s_waitcnt vmcnt(3)
	v_lshlrev_b32_e32 v62, 16, v46
	v_cvt_pk_bf16_f32 v16, v16, v17
	v_cvt_pk_bf16_f32 v17, v18, v19
	v_and_b32_e32 v250, 63, v203
	v_and_b32_e32 v251, 3, v250
	v_lshrrev_b32_e32 v252, 4, v250
	v_bfe_u32 v253, v250, 2, 2
	v_lshl_add_u32 v252, v252, 2, v253
	v_lshl_add_u32 v250, v251, 4, v252
	v_lshlrev_b32_e32 v250, 2, v250
	ds_bpermute_b32 v246, v250, v32
	ds_bpermute_b32 v247, v250, v33
	ds_bpermute_b32 v248, v250, v28
	ds_bpermute_b32 v249, v250, v29
	s_waitcnt lgkmcnt(0)
	global_store_dwordx2 v[246:247], v[248:249], off
	ds_bpermute_b32 v246, v250, v32
	ds_bpermute_b32 v247, v250, v33
	ds_bpermute_b32 v248, v250, v12
	ds_bpermute_b32 v249, v250, v13
	s_waitcnt lgkmcnt(0)
	global_store_dwordx2 v[246:247], v[248:249], off offset:32
	ds_bpermute_b32 v246, v250, v32
	ds_bpermute_b32 v247, v250, v33
	ds_bpermute_b32 v248, v250, v14
	ds_bpermute_b32 v249, v250, v15
	s_waitcnt lgkmcnt(0)
	global_store_dwordx2 v[246:247], v[248:249], off offset:64
	ds_bpermute_b32 v246, v250, v32
	ds_bpermute_b32 v247, v250, v33
	ds_bpermute_b32 v248, v250, v16
	ds_bpermute_b32 v249, v250, v17
	s_waitcnt lgkmcnt(0)
	global_store_dwordx2 v[246:247], v[248:249], off offset:96
	v_and_b32_e32 v63, 0xffff0000, v46
	v_lshlrev_b32_e32 v14, 16, v47
	v_and_b32_e32 v15, 0xffff0000, v47
	v_pk_mul_f32 v[12:13], v[20:21], v[62:63]
	v_pk_mul_f32 v[14:15], v[22:23], v[14:15]
	v_cvt_pk_bf16_f32 v12, v12, v13
	v_cvt_pk_bf16_f32 v13, v14, v15
	v_lshl_add_u64 v[14:15], v[42:43], 0, v[64:65]
	ds_bpermute_b32 v246, v250, v14
	ds_bpermute_b32 v247, v250, v15
	ds_bpermute_b32 v248, v250, v12
	ds_bpermute_b32 v249, v250, v13
	s_waitcnt lgkmcnt(0)
	global_store_dwordx2 v[246:247], v[248:249], off
	v_pk_mul_f32 v[4:5], v[4:5], v[50:51] op_sel_hi:[1,0]
	s_waitcnt vmcnt(7)
	v_lshlrev_b32_e32 v12, 16, v52
	v_and_b32_e32 v13, 0xffff0000, v52
	v_pk_mul_f32 v[6:7], v[6:7], v[50:51] op_sel_hi:[1,0]
	v_pk_mul_f32 v[4:5], v[4:5], v[12:13]
	v_lshlrev_b32_e32 v12, 16, v53
	v_and_b32_e32 v13, 0xffff0000, v53
	v_pk_mul_f32 v[6:7], v[6:7], v[12:13]
	v_cvt_pk_bf16_f32 v4, v4, v5
	v_cvt_pk_bf16_f32 v5, v6, v7
	v_pk_mul_f32 v[6:7], v[8:9], v[50:51] op_sel_hi:[1,0]
	s_waitcnt vmcnt(6)
	v_lshlrev_b32_e32 v8, 16, v54
	v_and_b32_e32 v9, 0xffff0000, v54
	ds_bpermute_b32 v246, v250, v14
	ds_bpermute_b32 v247, v250, v15
	ds_bpermute_b32 v248, v250, v4
	ds_bpermute_b32 v249, v250, v5
	s_waitcnt lgkmcnt(0)
	global_store_dwordx2 v[246:247], v[248:249], off offset:32
	v_pk_mul_f32 v[4:5], v[10:11], v[50:51] op_sel_hi:[1,0]
	v_pk_mul_f32 v[6:7], v[6:7], v[8:9]
	v_lshlrev_b32_e32 v8, 16, v55
	v_and_b32_e32 v9, 0xffff0000, v55
	v_pk_mul_f32 v[4:5], v[4:5], v[8:9]
	v_cvt_pk_bf16_f32 v6, v6, v7
	v_cvt_pk_bf16_f32 v7, v4, v5
	v_pk_mul_f32 v[0:1], v[0:1], v[50:51] op_sel_hi:[1,0]
	s_waitcnt vmcnt(6)
	v_lshlrev_b32_e32 v4, 16, v44
	v_and_b32_e32 v5, 0xffff0000, v44
	v_pk_mul_f32 v[2:3], v[2:3], v[50:51] op_sel_hi:[1,0]
	v_pk_mul_f32 v[0:1], v[0:1], v[4:5]
	v_lshlrev_b32_e32 v4, 16, v45
	v_and_b32_e32 v5, 0xffff0000, v45
	v_pk_mul_f32 v[2:3], v[2:3], v[4:5]
	v_cvt_pk_bf16_f32 v0, v0, v1
	v_cvt_pk_bf16_f32 v1, v2, v3
	ds_bpermute_b32 v246, v250, v14
	ds_bpermute_b32 v247, v250, v15
	ds_bpermute_b32 v248, v250, v6
	ds_bpermute_b32 v249, v250, v7
	s_waitcnt lgkmcnt(0)
	global_store_dwordx2 v[246:247], v[248:249], off offset:64
	ds_bpermute_b32 v246, v250, v14
	ds_bpermute_b32 v247, v250, v15
	ds_bpermute_b32 v248, v250, v0
	ds_bpermute_b32 v249, v250, v1
	s_waitcnt lgkmcnt(0)
	global_store_dwordx2 v[246:247], v[248:249], off offset:96
	s_barrier
	s_cbranch_scc1 .LBB0_921

; DEVI unsigned pk_bf16(float lo, float hi) { const f32x2_t v = {lo, hi}; const bf16x2_t b = __builtin_convertvector(v, bf16x2_t); return __builtin_bit_cast(unsigned, b); }
; DEVI float bf_lo(unsigned u) { return __uint_as_float(u << 16); }
; DEVI float bf_hi(unsigned u) { return __uint_as_float(u & 0xffff0000u); }
; DEVI float shx(float v, int m) { return __shfl_xor(v, m); }
; template <int MODE, bool SAMPLE>
; DEVI void attn_unit(const Params& p, const int b, const int h, const int qt, unsigned char* smem) {
;     ...
;     if (active) {
;         const bf16_t* SU = (const bf16_t*)(p.ws + (MODE == 0 ? W_SUA : W_SUB));
;         bf16_t* OAB = (bf16_t*)(p.ws + W_OAB);
; #pragma unroll
;         for (int j = 0; j < 2; ++j) {
;             float inv = 1.0f;
;             if (MODE == 0) { float l = st_l[j]; l += shx(l, 16); l += shx(l, 32); inv = (l > 0.f) ? __builtin_amdgcn_rcpf(l) : 0.f; }
;             const int tok = tok0 + 16 * j + l15;
; #pragma unroll
;             for (int dt = 0; dt < 4; ++dt) {
;                 const int col = h * 64 + 16 * dt + 4 * g;
;                 const u32x2 su = *(const u32x2*)(SU + (size_t)tok * 512 + col);
;                 f32x4 o = O[dt][j] * inv;
;                 u32x2 ov; ov.x = pk_bf16(o[0] * bf_lo(su.x), o[1] * bf_hi(su.x)); ov.y = pk_bf16(o[2] * bf_lo(su.y), o[3] * bf_hi(su.y));
;                 *(u32x2*)(OAB + (MODE == 0 ? (size_t)0 : (size_t)NTOK * 512) + (size_t)tok * 512 + col) = ov;
;             }
.LBB0_938:
	s_or_b64 exec, exec, s[6:7]
	s_barrier
	s_and_saveexec_b64 s[0:1], vcc
	s_cbranch_execz .LBB0_889
	v_or_b32_e32 v36, s26, v75
	v_lshlrev_b64 v[32:33], 1, v[70:71]
	v_lshl_add_u64 v[34:35], s[14:15], 0, v[32:33]
	v_lshlrev_b32_e32 v64, 1, v36
	v_lshl_add_u64 v[34:35], v[34:35], 0, v[64:65]
	global_load_dwordx2 v[36:37], v[34:35], off
	global_load_dwordx2 v[38:39], v[34:35], off offset:32
	global_load_dwordx2 v[40:41], v[34:35], off offset:64
	s_nop 0
	global_load_dwordx2 v[34:35], v[34:35], off offset:96
	ds_bpermute_b32 v42, v98, v72
	ds_bpermute_b32 v43, v98, v73
	v_lshlrev_b64 v[46:47], 1, v[68:69]
	v_lshl_add_u64 v[48:49], s[14:15], 0, v[46:47]
	v_lshl_add_u64 v[32:33], s[16:17], 0, v[32:33]
	v_lshl_add_u64 v[32:33], v[32:33], 0, v[64:65]
	s_waitcnt lgkmcnt(0)
	v_pk_add_f32 v[42:43], v[72:73], v[42:43]
	ds_bpermute_b32 v44, v99, v42
	ds_bpermute_b32 v45, v99, v43
	s_waitcnt lgkmcnt(0)
	v_pk_add_f32 v[42:43], v[42:43], v[44:45]
	s_nop 0
	v_rcp_f32_e32 v50, v42
	v_cmp_lt_f32_e32 vcc, 0, v42
	v_lshl_add_u64 v[44:45], v[48:49], 0, v[64:65]
	s_waitcnt vmcnt(3)
	v_lshlrev_b32_e32 v48, 16, v36
	v_cndmask_b32_e32 v42, 0, v50, vcc
	v_pk_mul_f32 v[30:31], v[30:31], v[42:43] op_sel_hi:[1,0]
	v_pk_mul_f32 v[28:29], v[28:29], v[42:43] op_sel_hi:[1,0]
	v_and_b32_e32 v49, 0xffff0000, v36
	v_lshlrev_b32_e32 v36, 16, v37
	v_and_b32_e32 v37, 0xffff0000, v37
	v_pk_mul_f32 v[18:19], v[18:19], v[42:43] op_sel_hi:[1,0]
	v_pk_mul_f32 v[16:17], v[16:17], v[42:43] op_sel_hi:[1,0]
	v_pk_mul_f32 v[26:27], v[26:27], v[42:43] op_sel_hi:[1,0]
	v_pk_mul_f32 v[24:25], v[24:25], v[42:43] op_sel_hi:[1,0]
	v_pk_mul_f32 v[22:23], v[22:23], v[42:43] op_sel_hi:[1,0]
	v_pk_mul_f32 v[20:21], v[20:21], v[42:43] op_sel_hi:[1,0]
	s_waitcnt vmcnt(2)
	v_lshlrev_b32_e32 v50, 16, v38
	v_and_b32_e32 v51, 0xffff0000, v38
	v_lshlrev_b32_e32 v38, 16, v39
	v_and_b32_e32 v39, 0xffff0000, v39
	s_waitcnt vmcnt(1)
	v_lshlrev_b32_e32 v52, 16, v40
	v_and_b32_e32 v53, 0xffff0000, v40
	v_lshlrev_b32_e32 v40, 16, v41
	v_and_b32_e32 v41, 0xffff0000, v41
	s_waitcnt vmcnt(0)
	v_lshlrev_b32_e32 v54, 16, v34
	v_and_b32_e32 v55, 0xffff0000, v34
	v_lshlrev_b32_e32 v34, 16, v35
	v_and_b32_e32 v35, 0xffff0000, v35
	v_pk_mul_f32 v[28:29], v[28:29], v[48:49]
	v_pk_mul_f32 v[30:31], v[30:31], v[36:37]
	v_pk_mul_f32 v[16:17], v[16:17], v[50:51]
	v_pk_mul_f32 v[18:19], v[18:19], v[38:39]
	v_pk_mul_f32 v[24:25], v[24:25], v[52:53]
	v_pk_mul_f32 v[26:27], v[26:27], v[40:41]
	v_pk_mul_f32 v[20:21], v[20:21], v[54:55]
	v_pk_mul_f32 v[22:23], v[22:23], v[34:35]
	v_cvt_pk_bf16_f32 v28, v28, v29
	v_cvt_pk_bf16_f32 v29, v30, v31
	v_cvt_pk_bf16_f32 v16, v16, v17
	v_cvt_pk_bf16_f32 v17, v18, v19
	v_cvt_pk_bf16_f32 v18, v24, v25
	v_cvt_pk_bf16_f32 v19, v26, v27
	v_cvt_pk_bf16_f32 v20, v20, v21
	v_cvt_pk_bf16_f32 v21, v22, v23
	v_and_b32_e32 v250, 63, v203
	v_and_b32_e32 v251, 3, v250
	v_lshrrev_b32_e32 v252, 4, v250
	v_bfe_u32 v253, v250, 2, 2
	v_lshl_add_u32 v252, v252, 2, v253
	v_lshl_add_u32 v250, v251, 4, v252
	v_lshlrev_b32_e32 v250, 2, v250
	ds_bpermute_b32 v246, v250, v32
	ds_bpermute_b32 v247, v250, v33
	ds_bpermute_b32 v248, v250, v28
	ds_bpermute_b32 v249, v250, v29
	s_waitcnt lgkmcnt(0)
	global_store_dwordx2 v[246:247], v[248:249], off
	ds_bpermute_b32 v246, v250, v32
	ds_bpermute_b32 v247, v250, v33
	ds_bpermute_b32 v248, v250, v16
	ds_bpermute_b32 v249, v250, v17
	s_waitcnt lgkmcnt(0)
	global_store_dwordx2 v[246:247], v[248:249], off offset:32
	ds_bpermute_b32 v246, v250, v32
	ds_bpermute_b32 v247, v250, v33
	ds_bpermute_b32 v248, v250, v18
	ds_bpermute_b32 v249, v250, v19
	s_waitcnt lgkmcnt(0)
	global_store_dwordx2 v[246:247], v[248:249], off offset:64
	ds_bpermute_b32 v246, v250, v32
	ds_bpermute_b32 v247, v250, v33
	ds_bpermute_b32 v248, v250, v20
	ds_bpermute_b32 v249, v250, v21
	s_waitcnt lgkmcnt(0)
	global_store_dwordx2 v[246:247], v[248:249], off offset:96
	global_load_dwordx2 v[16:17], v[44:45], off
	s_nop 0
	global_load_dwordx2 v[18:19], v[44:45], off offset:32
	global_load_dwordx2 v[20:21], v[44:45], off offset:64
	global_load_dwordx2 v[22:23], v[44:45], off offset:96
	v_rcp_f32_e32 v26, v43
	v_cmp_lt_f32_e32 vcc, 0, v43
	v_lshl_add_u64 v[24:25], s[16:17], 0, v[46:47]
	v_lshl_add_u64 v[24:25], v[24:25], 0, v[64:65]
	v_cndmask_b32_e32 v26, 0, v26, vcc
	v_pk_mul_f32 v[14:15], v[14:15], v[26:27] op_sel_hi:[1,0]
	v_pk_mul_f32 v[12:13], v[12:13], v[26:27] op_sel_hi:[1,0]
	v_pk_mul_f32 v[6:7], v[6:7], v[26:27] op_sel_hi:[1,0]
	v_pk_mul_f32 v[4:5], v[4:5], v[26:27] op_sel_hi:[1,0]
	v_pk_mul_f32 v[10:11], v[10:11], v[26:27] op_sel_hi:[1,0]
	v_pk_mul_f32 v[8:9], v[8:9], v[26:27] op_sel_hi:[1,0]
	v_pk_mul_f32 v[2:3], v[2:3], v[26:27] op_sel_hi:[1,0]
	v_pk_mul_f32 v[0:1], v[0:1], v[26:27] op_sel_hi:[1,0]
	s_waitcnt vmcnt(3)
	v_lshlrev_b32_e32 v26, 16, v16
	v_and_b32_e32 v27, 0xffff0000, v16
	v_lshlrev_b32_e32 v16, 16, v17
	v_and_b32_e32 v17, 0xffff0000, v17
	s_waitcnt vmcnt(2)
	v_lshlrev_b32_e32 v28, 16, v18
	v_and_b32_e32 v29, 0xffff0000, v18
	v_lshlrev_b32_e32 v18, 16, v19
	v_and_b32_e32 v19, 0xffff0000, v19
	s_waitcnt vmcnt(1)
	v_lshlrev_b32_e32 v30, 16, v20
	v_and_b32_e32 v31, 0xffff0000, v20
	v_lshlrev_b32_e32 v20, 16, v21
	v_and_b32_e32 v21, 0xffff0000, v21
	s_waitcnt vmcnt(0)
	v_lshlrev_b32_e32 v32, 16, v22
	v_and_b32_e32 v33, 0xffff0000, v22
	v_lshlrev_b32_e32 v22, 16, v23
	v_and_b32_e32 v23, 0xffff0000, v23
	v_pk_mul_f32 v[12:13], v[12:13], v[26:27]
	v_pk_mul_f32 v[14:15], v[14:15], v[16:17]
	v_pk_mul_f32 v[4:5], v[4:5], v[28:29]
	v_pk_mul_f32 v[6:7], v[6:7], v[18:19]
	v_pk_mul_f32 v[8:9], v[8:9], v[30:31]
	v_pk_mul_f32 v[10:11], v[10:11], v[20:21]
	v_pk_mul_f32 v[0:1], v[0:1], v[32:33]
	v_pk_mul_f32 v[2:3], v[2:3], v[22:23]
	v_cvt_pk_bf16_f32 v12, v12, v13
	v_cvt_pk_bf16_f32 v13, v14, v15
	v_cvt_pk_bf16_f32 v4, v4, v5
	v_cvt_pk_bf16_f32 v5, v6, v7
	v_cvt_pk_bf16_f32 v6, v8, v9
	v_cvt_pk_bf16_f32 v7, v10, v11
	v_cvt_pk_bf16_f32 v0, v0, v1
	v_cvt_pk_bf16_f32 v1, v2, v3
	ds_bpermute_b32 v246, v250, v24
	ds_bpermute_b32 v247, v250, v25
	ds_bpermute_b32 v248, v250, v12
	ds_bpermute_b32 v249, v250, v13
	s_waitcnt lgkmcnt(0)
	global_store_dwordx2 v[246:247], v[248:249], off
	ds_bpermute_b32 v246, v250, v24
	ds_bpermute_b32 v247, v250, v25
	ds_bpermute_b32 v248, v250, v4
	ds_bpermute_b32 v249, v250, v5
	s_waitcnt lgkmcnt(0)
	global_store_dwordx2 v[246:247], v[248:249], off offset:32
	ds_bpermute_b32 v246, v250, v24
	ds_bpermute_b32 v247, v250, v25
	ds_bpermute_b32 v248, v250, v6
	ds_bpermute_b32 v249, v250, v7
	s_waitcnt lgkmcnt(0)
	global_store_dwordx2 v[246:247], v[248:249], off offset:64
	ds_bpermute_b32 v246, v250, v24
	ds_bpermute_b32 v247, v250, v25
	ds_bpermute_b32 v248, v250, v0
	ds_bpermute_b32 v249, v250, v1
	s_waitcnt lgkmcnt(0)
	global_store_dwordx2 v[246:247], v[248:249], off offset:96
	s_branch .LBB0_889
